# f1 + DPP quad_perm neighbour exchange instead of ds_bpermute in the KV up-projection epilogue
# speedup vs baseline: 1.0089x; 1.0072x over previous
; __device__ __forceinline__ unsigned cvt_pk_bf16(float lo, float hi) { f32x2 v = {lo, hi}; bf16x2_t b = __builtin_convertvector(v, bf16x2_t); return __builtin_bit_cast(unsigned, b); }
;     __device__ __forceinline__ void operator()(const Acc& acc, const pg8::Unit& u, int wr, int wc, int fr, int fq) const {
;         const int row0 = u.pm * 256 + wr * 64 + fr, h = u.pn;
; #pragma unroll
;         for (int ai = 0; ai < 2; ++ai)
; #pragma unroll
;             for (int m = 0; m < 4; ++m) {
;                 const int row = row0 + ai * 128 + m * 16, b = row >> 12, s = row & 4095;
;                 const f32x4 s0 = *(const f32x4*)(stat + (size_t)row * 16 + 8), s1 = *(const f32x4*)(stat + (size_t)row * 16 + 12);
;                 const float rs = rsqrtf(((s0[0] + s0[1]) + (s0[2] + s0[3]) + (s1[0] + s1[1]) + (s1[2] + s1[3])) * (1.0f / 512.0f) + EPS);
;                 const size_t bh = (size_t)(b * 8 + h);
;                 *(u32x4*)(KN + (bh * 4096 + s) * 128 + wc * 32 + 8 * fq) = pack8(acc[ai][0][m][0] * rs, acc[ai][0][m][1] * rs);
;                 { const unsigned q0 = cvt_pk_bf16(acc[ai][1][m][0][0] * rs, acc[ai][1][m][0][1] * rs), q1 = cvt_pk_bf16(acc[ai][1][m][0][2] * rs, acc[ai][1][m][0][3] * rs),
;                                  q2 = cvt_pk_bf16(acc[ai][1][m][1][0] * rs, acc[ai][1][m][1][1] * rs), q3 = cvt_pk_bf16(acc[ai][1][m][1][2] * rs, acc[ai][1][m][1][3] * rs);
;                   const bool odd = fr & 1;
;                   const unsigned mine0 = odd ? q2 : q0, mine1 = odd ? q3 : q1, send0 = odd ? q0 : q2, send1 = odd ? q1 : q3;
;                   const unsigned oth0 = (unsigned)__shfl_xor((int)send0, 1), oth1 = (unsigned)__shfl_xor((int)send1, 1);
;                   const unsigned lo0 = odd ? oth0 : mine0, hi0 = odd ? mine0 : oth0, lo1 = odd ? oth1 : mine1, hi1 = odd ? mine1 : oth1;
;                   unsigned* vp = (unsigned*)(VT + (bh * 128 + wc * 32 + 8 * fq + (odd ? 4 : 0)) * 4096 + (s & ~1));
;                   vp[0 * 2048] = (lo0 & 0xffffu) | (hi0 << 16); vp[1 * 2048] = (lo0 >> 16) | (hi0 & 0xffff0000u);
;                   vp[2 * 2048] = (lo1 & 0xffffu) | (hi1 << 16); vp[3 * 2048] = (lo1 >> 16) | (hi1 & 0xffff0000u); }
.LBB0_726:
	s_mov_b32 s32, 1
	s_lshl_b32 s4, s33, 8
	s_add_i32 s4, s4, s65
	v_or_b32_e32 v152, s4, v159
	v_ashrrev_i32_e32 v153, 31, v152
	v_lshlrev_b64 v[154:155], 6, v[152:153]
	v_lshl_add_u64 v[154:155], s[10:11], 0, v[154:155]
	global_load_dwordx4 v[164:167], v[154:155], off offset:32
	global_load_dwordx4 v[168:171], v[154:155], off offset:48
	global_load_dwordx4 v[186:189], v[154:155], off offset:1056
	global_load_dwordx4 v[190:193], v[154:155], off offset:1072
	global_load_dwordx4 v[194:197], v[154:155], off offset:2080
	global_load_dwordx4 v[198:201], v[154:155], off offset:2096
	global_load_dwordx4 v[202:205], v[154:155], off offset:3104
	global_load_dwordx4 v[206:209], v[154:155], off offset:3120
	v_add_co_u32_e32 v242, vcc, 0x2000, v154
	s_nop 1
	v_addc_co_u32_e32 v243, vcc, 0, v155, vcc
	global_load_dwordx4 v[210:213], v[242:243], off offset:32
	global_load_dwordx4 v[214:217], v[242:243], off offset:48
	global_load_dwordx4 v[218:221], v[242:243], off offset:1056
	global_load_dwordx4 v[222:225], v[242:243], off offset:1072
	global_load_dwordx4 v[226:229], v[242:243], off offset:2080
	global_load_dwordx4 v[230:233], v[242:243], off offset:2096
	global_load_dwordx4 v[234:237], v[242:243], off offset:3104
	global_load_dwordx4 v[238:241], v[242:243], off offset:3120
	s_ashr_i32 s5, s4, 9
	v_and_b32_e32 v153, 64, v160
	v_bitop3_b32 v163, s4, v162, v159 bitop3:0xc8
	s_and_b32 s4, s5, -8
	v_xor_b32_e32 v138, 1, v160
	v_add_u32_e32 v153, 64, v153
	s_add_i32 s4, s4, s89
	v_cmp_lt_i32_e32 vcc, v138, v153
	v_or_b32_e32 v172, 16, v152
	s_ashr_i32 s5, s4, 31
	v_cndmask_b32_e32 v138, v160, v138, vcc
	v_ashrrev_i32_e32 v173, 31, v172
	s_lshl_b64 s[4:5], s[4:5], 20
	v_lshlrev_b32_e32 v153, 2, v138
	v_lshlrev_b32_e32 v138, 8, v152
	v_lshlrev_b64 v[154:155], 6, v[172:173]
	s_add_u32 s44, s16, s4
	v_and_b32_e32 v138, 0xfcf00, v138
	v_lshl_add_u64 v[174:175], s[10:11], 0, v[154:155]
	v_mov_b32_e32 v155, s5
	v_or_b32_e32 v154, s4, v140
	s_addc_u32 s45, s17, s5
	v_lshl_add_u64 v[154:155], s[18:19], 0, v[154:155]
	v_lshl_add_u64 v[176:177], s[44:45], 0, v[138:139]
	v_lshlrev_b32_e32 v138, 1, v163
	v_lshl_add_u64 v[178:179], v[154:155], 0, v[138:139]
	v_add_co_u32_e32 v180, vcc, s62, v178
	v_mov_b32_e32 v151, v139
	s_nop 0
	v_addc_co_u32_e32 v181, vcc, 0, v179, vcc
	v_add_co_u32_e32 v182, vcc, s63, v178
	v_lshl_add_u64 v[176:177], v[176:177], 0, s[12:13]
	s_nop 0
	v_addc_co_u32_e32 v183, vcc, 0, v179, vcc
	v_lshl_add_u64 v[176:177], v[176:177], 0, v[150:151]
	s_waitcnt vmcnt(0)
	v_mov_b32_e32 v184, v165
	v_mov_b32_e32 v185, v166
	v_mov_b32_e32 v165, v167
	v_mov_b32_e32 v166, v170
	v_mov_b32_e32 v167, v168
	v_mov_b32_e32 v168, v171
	v_pk_add_f32 v[164:165], v[184:185], v[164:165]
	v_pk_add_f32 v[166:167], v[166:167], v[168:169]
	v_add_f32_e32 v138, v164, v165
	v_add_f32_e32 v138, v138, v167
	v_add_f32_e32 v138, v166, v138
	v_fmamk_f32 v138, v138, 0x3b000000, v161
	v_mul_f32_e32 v163, 0x4b800000, v138
	v_cmp_gt_f32_e32 vcc, s81, v138
	v_add_co_u32_e64 v164, s[4:5], s64, v178
	s_nop 0
	v_cndmask_b32_e32 v138, v138, v163, vcc
	v_rsq_f32_e32 v138, v138
	v_addc_co_u32_e64 v165, s[4:5], 0, v179, s[4:5]
	v_mul_f32_e32 v163, 0x45800000, v138
	v_cndmask_b32_e32 v138, v138, v163, vcc
	v_pk_mul_f32 v[118:119], v[118:119], v[138:139] op_sel_hi:[1,0]
	v_pk_mul_f32 v[120:121], v[120:121], v[138:139] op_sel_hi:[1,0]
	v_pk_mul_f32 v[166:167], v[114:115], v[138:139] op_sel_hi:[1,0]
	v_pk_mul_f32 v[168:169], v[116:117], v[138:139] op_sel_hi:[1,0]
	v_cvt_pk_bf16_f32 v118, v118, v119
	v_cvt_pk_bf16_f32 v119, v120, v121
	v_cvt_pk_bf16_f32 v120, v166, v167
	v_pk_mul_f32 v[122:123], v[122:123], v[138:139] op_sel_hi:[1,0]
	v_cvt_pk_bf16_f32 v121, v168, v169
	v_cndmask_b32_e64 v117, v118, v120, s[0:1]
	v_cvt_pk_bf16_f32 v116, v122, v123
	s_nop 1
	v_mov_b32_dpp v122, v117 quad_perm:[1,0,3,2] row_mask:0xf bank_mask:0xf
	v_cndmask_b32_e64 v117, v119, v121, s[0:1]
	s_nop 1
	v_mov_b32_dpp v123, v117 quad_perm:[1,0,3,2] row_mask:0xf bank_mask:0xf
	v_pk_mul_f32 v[128:129], v[128:129], v[138:139] op_sel_hi:[1,0]
	v_pk_mul_f32 v[126:127], v[126:127], v[138:139] op_sel_hi:[1,0]
	v_pk_mul_f32 v[124:125], v[124:125], v[138:139] op_sel_hi:[1,0]
	v_cvt_pk_bf16_f32 v114, v126, v127
	v_cvt_pk_bf16_f32 v115, v128, v129
	v_cvt_pk_bf16_f32 v117, v124, v125
	global_store_dwordx4 v[176:177], v[114:117], off
	v_lshlrev_b32_e32 v126, 8, v172
	v_bitop3_b32 v128, v152, s84, 16 bitop3:0xc8
	s_waitcnt lgkmcnt(1)
	v_cndmask_b32_e64 v115, v120, v122, s[0:1]
	v_cndmask_b32_e64 v114, v122, v118, s[0:1]
	s_waitcnt lgkmcnt(0)
; __device__ __forceinline__ unsigned cvt_pk_bf16(float lo, float hi) { f32x2 v = {lo, hi}; bf16x2_t b = __builtin_convertvector(v, bf16x2_t); return __builtin_bit_cast(unsigned, b); }
;     __device__ __forceinline__ void operator()(const Acc& acc, const pg8::Unit& u, int wr, int wc, int fr, int fq) const {
;     ...
;                 const int row = row0 + ai * 128 + m * 16, b = row >> 12, s = row & 4095;
;                 const f32x4 s0 = *(const f32x4*)(stat + (size_t)row * 16 + 8), s1 = *(const f32x4*)(stat + (size_t)row * 16 + 12);
;                 const float rs = rsqrtf(((s0[0] + s0[1]) + (s0[2] + s0[3]) + (s1[0] + s1[1]) + (s1[2] + s1[3])) * (1.0f / 512.0f) + EPS);
;                 const size_t bh = (size_t)(b * 8 + h);
;                 *(u32x4*)(KN + (bh * 4096 + s) * 128 + wc * 32 + 8 * fq) = pack8(acc[ai][0][m][0] * rs, acc[ai][0][m][1] * rs);
;                 { const unsigned q0 = cvt_pk_bf16(acc[ai][1][m][0][0] * rs, acc[ai][1][m][0][1] * rs), q1 = cvt_pk_bf16(acc[ai][1][m][0][2] * rs, acc[ai][1][m][0][3] * rs),
;                                  q2 = cvt_pk_bf16(acc[ai][1][m][1][0] * rs, acc[ai][1][m][1][1] * rs), q3 = cvt_pk_bf16(acc[ai][1][m][1][2] * rs, acc[ai][1][m][1][3] * rs);
;                   const bool odd = fr & 1;
;                   const unsigned mine0 = odd ? q2 : q0, mine1 = odd ? q3 : q1, send0 = odd ? q0 : q2, send1 = odd ? q1 : q3;
;                   const unsigned oth0 = (unsigned)__shfl_xor((int)send0, 1), oth1 = (unsigned)__shfl_xor((int)send1, 1);
;                   const unsigned lo0 = odd ? oth0 : mine0, hi0 = odd ? mine0 : oth0, lo1 = odd ? oth1 : mine1, hi1 = odd ? mine1 : oth1;
;                   unsigned* vp = (unsigned*)(VT + (bh * 128 + wc * 32 + 8 * fq + (odd ? 4 : 0)) * 4096 + (s & ~1));
;                   vp[0 * 2048] = (lo0 & 0xffffu) | (hi0 << 16); vp[1 * 2048] = (lo0 >> 16) | (hi0 & 0xffff0000u);
;                   vp[2 * 2048] = (lo1 & 0xffffu) | (hi1 << 16); vp[3 * 2048] = (lo1 >> 16) | (hi1 & 0xffff0000u); }
	v_cndmask_b32_e64 v116, v123, v119, s[0:1]
	v_cndmask_b32_e64 v117, v121, v123, s[0:1]
	v_lshlrev_b32_e32 v118, 16, v115
	v_lshrrev_b32_e32 v119, 16, v114
	v_lshlrev_b32_e32 v120, 16, v117
	v_lshrrev_b32_e32 v121, 16, v116
	v_and_or_b32 v114, v114, s82, v118
	v_and_or_b32 v115, v115, s83, v119
	v_and_or_b32 v116, v116, s82, v120
	v_and_or_b32 v117, v117, s83, v121
	global_store_dword v[178:179], v114, off
	global_store_dword v[180:181], v115, off
	global_store_dword v[182:183], v116, off
	global_store_dword v[164:165], v117, off
	v_and_b32_e32 v138, 0xfdf00, v126
	v_lshl_add_u64 v[126:127], s[44:45], 0, v[138:139]
	v_lshlrev_b32_e32 v138, 1, v128
	v_lshl_add_u64 v[128:129], v[154:155], 0, v[138:139]
	v_add_co_u32_e32 v164, vcc, s62, v128
	v_lshl_add_u64 v[126:127], v[126:127], 0, s[12:13]
	s_nop 0
	v_addc_co_u32_e32 v165, vcc, 0, v129, vcc
	v_add_co_u32_e32 v166, vcc, s63, v128
	v_lshl_add_u64 v[126:127], v[126:127], 0, v[150:151]
	s_nop 0
	v_addc_co_u32_e32 v167, vcc, 0, v129, vcc
	v_or_b32_e32 v122, 32, v152
	v_ashrrev_i32_e32 v123, 31, v122
	v_lshlrev_b64 v[124:125], 6, v[122:123]
	v_lshl_add_u64 v[124:125], s[10:11], 0, v[124:125]
	v_mov_b32_e32 v114, v186
	v_mov_b32_e32 v115, v187
	v_mov_b32_e32 v116, v188
	v_mov_b32_e32 v117, v189
	v_mov_b32_e32 v168, v115
	v_mov_b32_e32 v169, v116
	v_mov_b32_e32 v115, v117
	v_mov_b32_e32 v118, v190
	v_mov_b32_e32 v119, v191
	v_mov_b32_e32 v120, v192
	v_mov_b32_e32 v121, v193
	v_mov_b32_e32 v116, v120
	v_mov_b32_e32 v117, v118
	v_mov_b32_e32 v118, v121
	v_pk_add_f32 v[114:115], v[168:169], v[114:115]
	v_pk_add_f32 v[116:117], v[116:117], v[118:119]
	v_add_f32_e32 v114, v114, v115
	v_add_f32_e32 v114, v114, v117
	v_add_f32_e32 v114, v116, v114
	v_fmamk_f32 v114, v114, 0x3b000000, v161
	v_mul_f32_e32 v115, 0x4b800000, v114
	v_cmp_gt_f32_e32 vcc, s81, v114
	s_nop 1
	v_cndmask_b32_e32 v114, v114, v115, vcc
	v_rsq_f32_e32 v116, v114
	v_add_co_u32_e64 v114, s[4:5], s64, v128
	v_mul_f32_e32 v117, 0x45800000, v116
	v_cndmask_b32_e32 v116, v116, v117, vcc
	v_pk_mul_f32 v[102:103], v[102:103], v[116:117] op_sel_hi:[1,0]
	v_pk_mul_f32 v[104:105], v[104:105], v[116:117] op_sel_hi:[1,0]
	v_pk_mul_f32 v[118:119], v[98:99], v[116:117] op_sel_hi:[1,0]
	v_pk_mul_f32 v[112:113], v[112:113], v[116:117] op_sel_hi:[1,0]
	v_pk_mul_f32 v[110:111], v[110:111], v[116:117] op_sel_hi:[1,0]
	v_pk_mul_f32 v[108:109], v[108:109], v[116:117] op_sel_hi:[1,0]
	v_pk_mul_f32 v[106:107], v[106:107], v[116:117] op_sel_hi:[1,0]
	v_pk_mul_f32 v[116:117], v[100:101], v[116:117] op_sel_hi:[1,0]
	v_cvt_pk_bf16_f32 v102, v102, v103
	v_cvt_pk_bf16_f32 v103, v104, v105
	v_cvt_pk_bf16_f32 v104, v118, v119
	v_cvt_pk_bf16_f32 v105, v116, v117
	v_cndmask_b32_e64 v101, v102, v104, s[0:1]
	v_cvt_pk_bf16_f32 v100, v106, v107
	s_nop 1
	v_mov_b32_dpp v106, v101 quad_perm:[1,0,3,2] row_mask:0xf bank_mask:0xf
	v_cndmask_b32_e64 v101, v103, v105, s[0:1]
	s_nop 1
	v_mov_b32_dpp v107, v101 quad_perm:[1,0,3,2] row_mask:0xf bank_mask:0xf
	v_cvt_pk_bf16_f32 v98, v110, v111
	v_cvt_pk_bf16_f32 v99, v112, v113
	v_cvt_pk_bf16_f32 v101, v108, v109
	global_store_dwordx4 v[126:127], v[98:101], off
	v_addc_co_u32_e64 v115, s[4:5], 0, v129, s[4:5]
	s_waitcnt lgkmcnt(1)
	v_cndmask_b32_e64 v99, v104, v106, s[0:1]
	v_cndmask_b32_e64 v98, v106, v102, s[0:1]
	s_waitcnt lgkmcnt(0)
	v_cndmask_b32_e64 v100, v107, v103, s[0:1]
	v_cndmask_b32_e64 v101, v105, v107, s[0:1]
	v_lshlrev_b32_e32 v102, 16, v99
	v_lshrrev_b32_e32 v103, 16, v98
	v_lshlrev_b32_e32 v104, 16, v101
	v_lshrrev_b32_e32 v105, 16, v100
	v_and_or_b32 v98, v98, s82, v102
	v_and_or_b32 v99, v99, s83, v103
	v_and_or_b32 v100, v100, s82, v104
	v_and_or_b32 v101, v101, s83, v105
	global_store_dword v[128:129], v98, off
	global_store_dword v[164:165], v99, off
	global_store_dword v[166:167], v100, off
	global_store_dword v[114:115], v101, off
	v_lshlrev_b32_e32 v110, 8, v122
	v_bitop3_b32 v112, v152, s85, 32 bitop3:0xc8
	v_and_b32_e32 v138, 0xfef00, v110
	v_lshl_add_u64 v[110:111], s[44:45], 0, v[138:139]
	v_lshlrev_b32_e32 v138, 1, v112
	v_lshl_add_u64 v[112:113], v[154:155], 0, v[138:139]
	v_add_co_u32_e32 v114, vcc, s62, v112
	v_lshl_add_u64 v[110:111], v[110:111], 0, s[12:13]
	s_nop 0
	v_addc_co_u32_e32 v115, vcc, 0, v113, vcc
	v_add_co_u32_e32 v116, vcc, s63, v112
	v_lshl_add_u64 v[110:111], v[110:111], 0, v[150:151]
	s_nop 0
	v_addc_co_u32_e32 v117, vcc, 0, v113, vcc
	v_or_b32_e32 v106, 48, v152
	v_ashrrev_i32_e32 v107, 31, v106
	v_lshlrev_b64 v[108:109], 6, v[106:107]
	v_lshl_add_u64 v[108:109], s[10:11], 0, v[108:109]
	v_mov_b32_e32 v98, v194
	v_mov_b32_e32 v99, v195
	v_mov_b32_e32 v100, v196
	v_mov_b32_e32 v101, v197
	v_mov_b32_e32 v118, v99
	v_mov_b32_e32 v119, v100
	v_mov_b32_e32 v99, v101
	v_mov_b32_e32 v102, v198
	v_mov_b32_e32 v103, v199
	v_mov_b32_e32 v104, v200
	v_mov_b32_e32 v105, v201
	v_mov_b32_e32 v100, v104
	v_mov_b32_e32 v101, v102
	v_mov_b32_e32 v102, v105
	v_pk_add_f32 v[98:99], v[118:119], v[98:99]
	v_pk_add_f32 v[100:101], v[100:101], v[102:103]
	v_add_f32_e32 v98, v98, v99
	v_add_f32_e32 v98, v98, v101
	v_add_f32_e32 v98, v100, v98
	v_fmamk_f32 v98, v98, 0x3b000000, v161
	v_mul_f32_e32 v99, 0x4b800000, v98
	v_cmp_gt_f32_e32 vcc, s81, v98
	s_nop 1
	v_cndmask_b32_e32 v98, v98, v99, vcc
	v_rsq_f32_e32 v100, v98
	v_add_co_u32_e64 v98, s[4:5], s64, v112
	v_mul_f32_e32 v101, 0x45800000, v100
	v_cndmask_b32_e32 v100, v100, v101, vcc
	v_pk_mul_f32 v[86:87], v[86:87], v[100:101] op_sel_hi:[1,0]
	v_pk_mul_f32 v[88:89], v[88:89], v[100:101] op_sel_hi:[1,0]
	v_pk_mul_f32 v[102:103], v[82:83], v[100:101] op_sel_hi:[1,0]
	v_pk_mul_f32 v[96:97], v[96:97], v[100:101] op_sel_hi:[1,0]
	v_pk_mul_f32 v[94:95], v[94:95], v[100:101] op_sel_hi:[1,0]
	v_pk_mul_f32 v[92:93], v[92:93], v[100:101] op_sel_hi:[1,0]
	v_pk_mul_f32 v[90:91], v[90:91], v[100:101] op_sel_hi:[1,0]
	v_pk_mul_f32 v[100:101], v[84:85], v[100:101] op_sel_hi:[1,0]
	v_cvt_pk_bf16_f32 v86, v86, v87
	v_cvt_pk_bf16_f32 v87, v88, v89
	v_cvt_pk_bf16_f32 v88, v102, v103
	v_cvt_pk_bf16_f32 v89, v100, v101
	v_cndmask_b32_e64 v85, v86, v88, s[0:1]
	v_cvt_pk_bf16_f32 v84, v90, v91
	s_nop 1
	v_mov_b32_dpp v90, v85 quad_perm:[1,0,3,2] row_mask:0xf bank_mask:0xf
	v_cndmask_b32_e64 v85, v87, v89, s[0:1]
	s_nop 1
	v_mov_b32_dpp v91, v85 quad_perm:[1,0,3,2] row_mask:0xf bank_mask:0xf
	v_cvt_pk_bf16_f32 v82, v94, v95
	v_cvt_pk_bf16_f32 v83, v96, v97
	v_cvt_pk_bf16_f32 v85, v92, v93
	global_store_dwordx4 v[110:111], v[82:85], off
	v_addc_co_u32_e64 v99, s[4:5], 0, v113, s[4:5]
	s_waitcnt lgkmcnt(1)
; __device__ __forceinline__ unsigned cvt_pk_bf16(float lo, float hi) { f32x2 v = {lo, hi}; bf16x2_t b = __builtin_convertvector(v, bf16x2_t); return __builtin_bit_cast(unsigned, b); }
;     __device__ __forceinline__ void operator()(const Acc& acc, const pg8::Unit& u, int wr, int wc, int fr, int fq) const {
;         const int row0 = u.pm * 256 + wr * 64 + fr, h = u.pn;
; #pragma unroll
;         for (int ai = 0; ai < 2; ++ai)
; #pragma unroll
;             for (int m = 0; m < 4; ++m) {
;                 const int row = row0 + ai * 128 + m * 16, b = row >> 12, s = row & 4095;
;                 const f32x4 s0 = *(const f32x4*)(stat + (size_t)row * 16 + 8), s1 = *(const f32x4*)(stat + (size_t)row * 16 + 12);
;                 const float rs = rsqrtf(((s0[0] + s0[1]) + (s0[2] + s0[3]) + (s1[0] + s1[1]) + (s1[2] + s1[3])) * (1.0f / 512.0f) + EPS);
;                 const size_t bh = (size_t)(b * 8 + h);
;                 *(u32x4*)(KN + (bh * 4096 + s) * 128 + wc * 32 + 8 * fq) = pack8(acc[ai][0][m][0] * rs, acc[ai][0][m][1] * rs);
;                 { const unsigned q0 = cvt_pk_bf16(acc[ai][1][m][0][0] * rs, acc[ai][1][m][0][1] * rs), q1 = cvt_pk_bf16(acc[ai][1][m][0][2] * rs, acc[ai][1][m][0][3] * rs),
;                                  q2 = cvt_pk_bf16(acc[ai][1][m][1][0] * rs, acc[ai][1][m][1][1] * rs), q3 = cvt_pk_bf16(acc[ai][1][m][1][2] * rs, acc[ai][1][m][1][3] * rs);
;                   const bool odd = fr & 1;
;                   const unsigned mine0 = odd ? q2 : q0, mine1 = odd ? q3 : q1, send0 = odd ? q0 : q2, send1 = odd ? q1 : q3;
;                   const unsigned oth0 = (unsigned)__shfl_xor((int)send0, 1), oth1 = (unsigned)__shfl_xor((int)send1, 1);
;                   const unsigned lo0 = odd ? oth0 : mine0, hi0 = odd ? mine0 : oth0, lo1 = odd ? oth1 : mine1, hi1 = odd ? mine1 : oth1;
;                   unsigned* vp = (unsigned*)(VT + (bh * 128 + wc * 32 + 8 * fq + (odd ? 4 : 0)) * 4096 + (s & ~1));
;                   vp[0 * 2048] = (lo0 & 0xffffu) | (hi0 << 16); vp[1 * 2048] = (lo0 >> 16) | (hi0 & 0xffff0000u);
;                   vp[2 * 2048] = (lo1 & 0xffffu) | (hi1 << 16); vp[3 * 2048] = (lo1 >> 16) | (hi1 & 0xffff0000u); }
	v_cndmask_b32_e64 v83, v88, v90, s[0:1]
	v_cndmask_b32_e64 v82, v90, v86, s[0:1]
	s_waitcnt lgkmcnt(0)
	v_cndmask_b32_e64 v84, v91, v87, s[0:1]
	v_cndmask_b32_e64 v85, v89, v91, s[0:1]
	v_lshlrev_b32_e32 v86, 16, v83
	v_lshrrev_b32_e32 v87, 16, v82
	v_lshlrev_b32_e32 v88, 16, v85
	v_lshrrev_b32_e32 v89, 16, v84
	v_and_or_b32 v82, v82, s82, v86
	v_and_or_b32 v83, v83, s83, v87
	v_and_or_b32 v84, v84, s82, v88
	v_and_or_b32 v85, v85, s83, v89
	global_store_dword v[112:113], v82, off
	global_store_dword v[114:115], v83, off
	global_store_dword v[116:117], v84, off
	global_store_dword v[98:99], v85, off
	v_lshlrev_b32_e32 v94, 8, v106
	v_bitop3_b32 v96, v152, s86, 48 bitop3:0xc8
	v_and_b32_e32 v138, 0xfff00, v94
	v_lshl_add_u64 v[94:95], s[44:45], 0, v[138:139]
	v_lshlrev_b32_e32 v138, 1, v96
	v_lshl_add_u64 v[96:97], v[154:155], 0, v[138:139]
	v_add_co_u32_e32 v98, vcc, s62, v96
	v_lshl_add_u64 v[94:95], v[94:95], 0, s[12:13]
	s_nop 0
	v_addc_co_u32_e32 v99, vcc, 0, v97, vcc
	v_add_co_u32_e32 v100, vcc, s63, v96
	v_lshl_add_u64 v[94:95], v[94:95], 0, v[150:151]
	s_nop 0
	v_addc_co_u32_e32 v101, vcc, 0, v97, vcc
	v_add_u32_e32 v90, 0x80, v152
	v_ashrrev_i32_e32 v91, 31, v90
	v_lshlrev_b64 v[92:93], 6, v[90:91]
	v_lshl_add_u64 v[92:93], s[10:11], 0, v[92:93]
	v_mov_b32_e32 v82, v202
	v_mov_b32_e32 v83, v203
	v_mov_b32_e32 v84, v204
	v_mov_b32_e32 v85, v205
	v_mov_b32_e32 v102, v83
	v_mov_b32_e32 v103, v84
	v_mov_b32_e32 v83, v85
	v_mov_b32_e32 v86, v206
	v_mov_b32_e32 v87, v207
	v_mov_b32_e32 v88, v208
	v_mov_b32_e32 v89, v209
	v_mov_b32_e32 v84, v88
	v_mov_b32_e32 v85, v86
	v_mov_b32_e32 v86, v89
	v_pk_add_f32 v[82:83], v[102:103], v[82:83]
	v_pk_add_f32 v[84:85], v[84:85], v[86:87]
	v_add_f32_e32 v82, v82, v83
	v_add_f32_e32 v82, v82, v85
	v_add_f32_e32 v82, v84, v82
	v_fmamk_f32 v82, v82, 0x3b000000, v161
	v_mul_f32_e32 v83, 0x4b800000, v82
	v_cmp_gt_f32_e32 vcc, s81, v82
	s_nop 1
	v_cndmask_b32_e32 v82, v82, v83, vcc
	v_rsq_f32_e32 v84, v82
	v_add_co_u32_e64 v82, s[4:5], s64, v96
	v_mul_f32_e32 v85, 0x45800000, v84
	v_cndmask_b32_e32 v84, v84, v85, vcc
	v_pk_mul_f32 v[70:71], v[70:71], v[84:85] op_sel_hi:[1,0]
	v_pk_mul_f32 v[72:73], v[72:73], v[84:85] op_sel_hi:[1,0]
	v_pk_mul_f32 v[86:87], v[66:67], v[84:85] op_sel_hi:[1,0]
	v_pk_mul_f32 v[80:81], v[80:81], v[84:85] op_sel_hi:[1,0]
	v_pk_mul_f32 v[78:79], v[78:79], v[84:85] op_sel_hi:[1,0]
	v_pk_mul_f32 v[76:77], v[76:77], v[84:85] op_sel_hi:[1,0]
	v_pk_mul_f32 v[74:75], v[74:75], v[84:85] op_sel_hi:[1,0]
	v_pk_mul_f32 v[84:85], v[68:69], v[84:85] op_sel_hi:[1,0]
	v_cvt_pk_bf16_f32 v70, v70, v71
	v_cvt_pk_bf16_f32 v71, v72, v73
	v_cvt_pk_bf16_f32 v72, v86, v87
	v_cvt_pk_bf16_f32 v73, v84, v85
	v_cndmask_b32_e64 v69, v70, v72, s[0:1]
	v_cvt_pk_bf16_f32 v68, v74, v75
	s_nop 1
	v_mov_b32_dpp v74, v69 quad_perm:[1,0,3,2] row_mask:0xf bank_mask:0xf
	v_cndmask_b32_e64 v69, v71, v73, s[0:1]
	s_nop 1
	v_mov_b32_dpp v75, v69 quad_perm:[1,0,3,2] row_mask:0xf bank_mask:0xf
	v_cvt_pk_bf16_f32 v66, v78, v79
	v_cvt_pk_bf16_f32 v67, v80, v81
	v_cvt_pk_bf16_f32 v69, v76, v77
	global_store_dwordx4 v[94:95], v[66:69], off
	v_addc_co_u32_e64 v83, s[4:5], 0, v97, s[4:5]
	s_waitcnt lgkmcnt(1)
	v_cndmask_b32_e64 v67, v72, v74, s[0:1]
	v_cndmask_b32_e64 v66, v74, v70, s[0:1]
	s_waitcnt lgkmcnt(0)
	v_cndmask_b32_e64 v68, v75, v71, s[0:1]
	v_cndmask_b32_e64 v69, v73, v75, s[0:1]
	v_lshlrev_b32_e32 v70, 16, v67
	v_lshrrev_b32_e32 v71, 16, v66
	v_lshlrev_b32_e32 v72, 16, v69
	v_lshrrev_b32_e32 v73, 16, v68
	v_and_or_b32 v66, v66, s82, v70
	v_and_or_b32 v67, v67, s83, v71
	v_and_or_b32 v68, v68, s82, v72
	v_and_or_b32 v69, v69, s83, v73
	global_store_dword v[96:97], v66, off
	global_store_dword v[98:99], v67, off
	global_store_dword v[100:101], v68, off
	global_store_dword v[82:83], v69, off
	v_ashrrev_i32_e32 v66, 9, v90
	v_add_u32_e32 v78, 0x90, v152
	v_and_b32_e32 v68, -8, v66
	v_ashrrev_i32_e32 v79, 31, v78
	v_add_u32_e32 v68, s89, v68
	v_lshlrev_b64 v[66:67], 6, v[78:79]
	v_ashrrev_i32_e32 v69, 31, v68
	v_lshlrev_b32_e32 v84, 8, v90
	v_lshl_add_u64 v[80:81], s[10:11], 0, v[66:67]
	v_lshlrev_b64 v[66:67], 20, v[68:69]
	v_and_b32_e32 v85, 0xfce, v90
	v_or_b32_e32 v82, v66, v140
	v_mov_b32_e32 v83, v67
	v_lshl_add_u64 v[68:69], s[16:17], 0, v[66:67]
	v_and_b32_e32 v138, 0xfcf00, v84
	v_lshl_add_u64 v[66:67], s[18:19], 0, v[82:83]
	v_lshl_add_u64 v[82:83], v[68:69], 0, v[138:139]
	v_lshlrev_b32_e32 v138, 1, v85
	v_lshl_add_u64 v[84:85], v[66:67], 0, v[138:139]
	v_add_co_u32_e32 v86, vcc, s62, v84
	v_lshl_add_u64 v[82:83], v[82:83], 0, s[12:13]
	s_nop 0
	v_addc_co_u32_e32 v87, vcc, 0, v85, vcc
	v_add_co_u32_e32 v88, vcc, s63, v84
	v_lshl_add_u64 v[82:83], v[82:83], 0, v[150:151]
	s_nop 0
	v_addc_co_u32_e32 v89, vcc, 0, v85, vcc
	v_mov_b32_e32 v70, v210
	v_mov_b32_e32 v71, v211
	v_mov_b32_e32 v72, v212
	v_mov_b32_e32 v73, v213
	v_mov_b32_e32 v90, v71
	v_mov_b32_e32 v91, v72
	v_mov_b32_e32 v71, v73
	v_mov_b32_e32 v74, v214
	v_mov_b32_e32 v75, v215
	v_mov_b32_e32 v76, v216
	v_mov_b32_e32 v77, v217
	v_mov_b32_e32 v72, v76
	v_mov_b32_e32 v73, v74
	v_mov_b32_e32 v74, v77
	v_pk_add_f32 v[70:71], v[90:91], v[70:71]
	v_pk_add_f32 v[72:73], v[72:73], v[74:75]
	v_add_f32_e32 v70, v70, v71
	v_add_f32_e32 v70, v70, v73
	v_add_f32_e32 v70, v72, v70
	v_fmamk_f32 v70, v70, 0x3b000000, v161
	v_mul_f32_e32 v71, 0x4b800000, v70
	v_cmp_gt_f32_e32 vcc, s81, v70
	s_nop 1
	v_cndmask_b32_e32 v70, v70, v71, vcc
	v_rsq_f32_e32 v72, v70
	v_add_co_u32_e64 v70, s[4:5], s64, v84
	v_mul_f32_e32 v73, 0x45800000, v72
	v_cndmask_b32_e32 v72, v72, v73, vcc
	v_pk_mul_f32 v[54:55], v[54:55], v[72:73] op_sel_hi:[1,0]
	v_pk_mul_f32 v[56:57], v[56:57], v[72:73] op_sel_hi:[1,0]
	v_pk_mul_f32 v[74:75], v[50:51], v[72:73] op_sel_hi:[1,0]
	v_pk_mul_f32 v[64:65], v[64:65], v[72:73] op_sel_hi:[1,0]
	v_pk_mul_f32 v[62:63], v[62:63], v[72:73] op_sel_hi:[1,0]
	v_pk_mul_f32 v[60:61], v[60:61], v[72:73] op_sel_hi:[1,0]
	v_pk_mul_f32 v[58:59], v[58:59], v[72:73] op_sel_hi:[1,0]
	v_pk_mul_f32 v[72:73], v[52:53], v[72:73] op_sel_hi:[1,0]
	v_cvt_pk_bf16_f32 v54, v54, v55
	v_cvt_pk_bf16_f32 v55, v56, v57
	v_cvt_pk_bf16_f32 v56, v74, v75
	v_cvt_pk_bf16_f32 v57, v72, v73
	v_cndmask_b32_e64 v53, v54, v56, s[0:1]
	v_cvt_pk_bf16_f32 v52, v58, v59
	s_nop 1
	v_mov_b32_dpp v58, v53 quad_perm:[1,0,3,2] row_mask:0xf bank_mask:0xf
	v_cndmask_b32_e64 v53, v55, v57, s[0:1]
	s_nop 1
	v_mov_b32_dpp v59, v53 quad_perm:[1,0,3,2] row_mask:0xf bank_mask:0xf
	v_cvt_pk_bf16_f32 v50, v62, v63
	v_cvt_pk_bf16_f32 v51, v64, v65
	v_cvt_pk_bf16_f32 v53, v60, v61
	global_store_dwordx4 v[82:83], v[50:53], off
	v_addc_co_u32_e64 v71, s[4:5], 0, v85, s[4:5]
	s_waitcnt lgkmcnt(1)
; __device__ __forceinline__ unsigned cvt_pk_bf16(float lo, float hi) { f32x2 v = {lo, hi}; bf16x2_t b = __builtin_convertvector(v, bf16x2_t); return __builtin_bit_cast(unsigned, b); }
;     __device__ __forceinline__ void operator()(const Acc& acc, const pg8::Unit& u, int wr, int wc, int fr, int fq) const {
;     ...
;                 const int row = row0 + ai * 128 + m * 16, b = row >> 12, s = row & 4095;
;                 const f32x4 s0 = *(const f32x4*)(stat + (size_t)row * 16 + 8), s1 = *(const f32x4*)(stat + (size_t)row * 16 + 12);
;                 const float rs = rsqrtf(((s0[0] + s0[1]) + (s0[2] + s0[3]) + (s1[0] + s1[1]) + (s1[2] + s1[3])) * (1.0f / 512.0f) + EPS);
;                 const size_t bh = (size_t)(b * 8 + h);
;                 *(u32x4*)(KN + (bh * 4096 + s) * 128 + wc * 32 + 8 * fq) = pack8(acc[ai][0][m][0] * rs, acc[ai][0][m][1] * rs);
;                 { const unsigned q0 = cvt_pk_bf16(acc[ai][1][m][0][0] * rs, acc[ai][1][m][0][1] * rs), q1 = cvt_pk_bf16(acc[ai][1][m][0][2] * rs, acc[ai][1][m][0][3] * rs),
;                                  q2 = cvt_pk_bf16(acc[ai][1][m][1][0] * rs, acc[ai][1][m][1][1] * rs), q3 = cvt_pk_bf16(acc[ai][1][m][1][2] * rs, acc[ai][1][m][1][3] * rs);
;                   const bool odd = fr & 1;
;                   const unsigned mine0 = odd ? q2 : q0, mine1 = odd ? q3 : q1, send0 = odd ? q0 : q2, send1 = odd ? q1 : q3;
;                   const unsigned oth0 = (unsigned)__shfl_xor((int)send0, 1), oth1 = (unsigned)__shfl_xor((int)send1, 1);
;                   const unsigned lo0 = odd ? oth0 : mine0, hi0 = odd ? mine0 : oth0, lo1 = odd ? oth1 : mine1, hi1 = odd ? mine1 : oth1;
;                   unsigned* vp = (unsigned*)(VT + (bh * 128 + wc * 32 + 8 * fq + (odd ? 4 : 0)) * 4096 + (s & ~1));
;                   vp[0 * 2048] = (lo0 & 0xffffu) | (hi0 << 16); vp[1 * 2048] = (lo0 >> 16) | (hi0 & 0xffff0000u);
;                   vp[2 * 2048] = (lo1 & 0xffffu) | (hi1 << 16); vp[3 * 2048] = (lo1 >> 16) | (hi1 & 0xffff0000u); }
	v_cndmask_b32_e64 v51, v56, v58, s[0:1]
	v_cndmask_b32_e64 v50, v58, v54, s[0:1]
	s_waitcnt lgkmcnt(0)
	v_cndmask_b32_e64 v52, v59, v55, s[0:1]
	v_cndmask_b32_e64 v53, v57, v59, s[0:1]
	v_lshlrev_b32_e32 v54, 16, v51
	v_lshrrev_b32_e32 v55, 16, v50
	v_lshlrev_b32_e32 v56, 16, v53
	v_lshrrev_b32_e32 v57, 16, v52
	v_and_or_b32 v50, v50, s82, v54
	v_and_or_b32 v51, v51, s83, v55
	v_and_or_b32 v52, v52, s82, v56
	v_and_or_b32 v53, v53, s83, v57
	global_store_dword v[84:85], v50, off
	global_store_dword v[86:87], v51, off
	global_store_dword v[88:89], v52, off
	global_store_dword v[70:71], v53, off
	v_lshlrev_b32_e32 v62, 8, v78
	v_and_b32_e32 v64, 0xfde, v78
	v_and_b32_e32 v138, 0xfdf00, v62
	v_lshl_add_u64 v[62:63], v[68:69], 0, v[138:139]
	v_lshlrev_b32_e32 v138, 1, v64
	v_lshl_add_u64 v[64:65], v[66:67], 0, v[138:139]
	v_add_co_u32_e32 v70, vcc, s62, v64
	v_lshl_add_u64 v[62:63], v[62:63], 0, s[12:13]
	s_nop 0
	v_addc_co_u32_e32 v71, vcc, 0, v65, vcc
	v_add_co_u32_e32 v72, vcc, s63, v64
	v_lshl_add_u64 v[62:63], v[62:63], 0, v[150:151]
	s_nop 0
	v_addc_co_u32_e32 v73, vcc, 0, v65, vcc
	v_add_u32_e32 v58, 0xa0, v152
	v_ashrrev_i32_e32 v59, 31, v58
	v_lshlrev_b64 v[60:61], 6, v[58:59]
	v_lshl_add_u64 v[60:61], s[10:11], 0, v[60:61]
	v_mov_b32_e32 v50, v218
	v_mov_b32_e32 v51, v219
	v_mov_b32_e32 v52, v220
	v_mov_b32_e32 v53, v221
	v_mov_b32_e32 v74, v51
	v_mov_b32_e32 v75, v52
	v_mov_b32_e32 v51, v53
	v_mov_b32_e32 v54, v222
	v_mov_b32_e32 v55, v223
	v_mov_b32_e32 v56, v224
	v_mov_b32_e32 v57, v225
	v_mov_b32_e32 v52, v56
	v_mov_b32_e32 v53, v54
	v_mov_b32_e32 v54, v57
	v_pk_add_f32 v[50:51], v[74:75], v[50:51]
	v_pk_add_f32 v[52:53], v[52:53], v[54:55]
	v_add_f32_e32 v50, v50, v51
	v_add_f32_e32 v50, v50, v53
	v_add_f32_e32 v50, v52, v50
	v_fmamk_f32 v50, v50, 0x3b000000, v161
	v_mul_f32_e32 v51, 0x4b800000, v50
	v_cmp_gt_f32_e32 vcc, s81, v50
	s_nop 1
	v_cndmask_b32_e32 v50, v50, v51, vcc
	v_rsq_f32_e32 v52, v50
	v_add_co_u32_e64 v50, s[4:5], s64, v64
	v_mul_f32_e32 v53, 0x45800000, v52
	v_cndmask_b32_e32 v52, v52, v53, vcc
	v_pk_mul_f32 v[38:39], v[38:39], v[52:53] op_sel_hi:[1,0]
	v_pk_mul_f32 v[40:41], v[40:41], v[52:53] op_sel_hi:[1,0]
	v_pk_mul_f32 v[54:55], v[34:35], v[52:53] op_sel_hi:[1,0]
	v_pk_mul_f32 v[48:49], v[48:49], v[52:53] op_sel_hi:[1,0]
	v_pk_mul_f32 v[46:47], v[46:47], v[52:53] op_sel_hi:[1,0]
	v_pk_mul_f32 v[44:45], v[44:45], v[52:53] op_sel_hi:[1,0]
	v_pk_mul_f32 v[42:43], v[42:43], v[52:53] op_sel_hi:[1,0]
	v_pk_mul_f32 v[52:53], v[36:37], v[52:53] op_sel_hi:[1,0]
	v_cvt_pk_bf16_f32 v38, v38, v39
	v_cvt_pk_bf16_f32 v39, v40, v41
	v_cvt_pk_bf16_f32 v40, v54, v55
	v_cvt_pk_bf16_f32 v41, v52, v53
	v_cndmask_b32_e64 v37, v38, v40, s[0:1]
	v_cvt_pk_bf16_f32 v36, v42, v43
	s_nop 1
	v_mov_b32_dpp v42, v37 quad_perm:[1,0,3,2] row_mask:0xf bank_mask:0xf
	v_cndmask_b32_e64 v37, v39, v41, s[0:1]
	s_nop 1
	v_mov_b32_dpp v43, v37 quad_perm:[1,0,3,2] row_mask:0xf bank_mask:0xf
	v_cvt_pk_bf16_f32 v34, v46, v47
	v_cvt_pk_bf16_f32 v35, v48, v49
	v_cvt_pk_bf16_f32 v37, v44, v45
	global_store_dwordx4 v[62:63], v[34:37], off
	v_addc_co_u32_e64 v51, s[4:5], 0, v65, s[4:5]
	s_waitcnt lgkmcnt(1)
	v_cndmask_b32_e64 v35, v40, v42, s[0:1]
	v_cndmask_b32_e64 v34, v42, v38, s[0:1]
	s_waitcnt lgkmcnt(0)
	v_cndmask_b32_e64 v36, v43, v39, s[0:1]
	v_cndmask_b32_e64 v37, v41, v43, s[0:1]
	v_lshlrev_b32_e32 v38, 16, v35
	v_lshrrev_b32_e32 v39, 16, v34
	v_lshlrev_b32_e32 v40, 16, v37
	v_lshrrev_b32_e32 v41, 16, v36
	v_and_or_b32 v34, v34, s82, v38
	v_and_or_b32 v35, v35, s83, v39
	v_and_or_b32 v36, v36, s82, v40
	v_and_or_b32 v37, v37, s83, v41
	global_store_dword v[64:65], v34, off
	global_store_dword v[70:71], v35, off
	global_store_dword v[72:73], v36, off
	global_store_dword v[50:51], v37, off
	v_lshlrev_b32_e32 v46, 8, v58
	v_and_b32_e32 v48, 0xfee, v58
	v_and_b32_e32 v138, 0xfef00, v46
	v_lshl_add_u64 v[46:47], v[68:69], 0, v[138:139]
	v_lshlrev_b32_e32 v138, 1, v48
	v_lshl_add_u64 v[48:49], v[66:67], 0, v[138:139]
	v_add_co_u32_e32 v50, vcc, s62, v48
	v_lshl_add_u64 v[46:47], v[46:47], 0, s[12:13]
	s_nop 0
	v_addc_co_u32_e32 v51, vcc, 0, v49, vcc
	v_add_co_u32_e32 v52, vcc, s63, v48
	v_lshl_add_u64 v[46:47], v[46:47], 0, v[150:151]
	s_nop 0
	v_addc_co_u32_e32 v53, vcc, 0, v49, vcc
	v_add_u32_e32 v42, 0xb0, v152
	v_ashrrev_i32_e32 v43, 31, v42
	v_lshlrev_b64 v[44:45], 6, v[42:43]
	v_lshl_add_u64 v[44:45], s[10:11], 0, v[44:45]
	v_mov_b32_e32 v34, v226
	v_mov_b32_e32 v35, v227
	v_mov_b32_e32 v36, v228
	v_mov_b32_e32 v37, v229
	v_mov_b32_e32 v54, v35
	v_mov_b32_e32 v55, v36
	v_mov_b32_e32 v35, v37
	v_mov_b32_e32 v38, v230
	v_mov_b32_e32 v39, v231
	v_mov_b32_e32 v40, v232
	v_mov_b32_e32 v41, v233
	v_mov_b32_e32 v36, v40
	v_mov_b32_e32 v37, v38
	v_mov_b32_e32 v38, v41
	v_pk_add_f32 v[34:35], v[54:55], v[34:35]
	v_pk_add_f32 v[36:37], v[36:37], v[38:39]
	v_add_f32_e32 v34, v34, v35
	v_add_f32_e32 v34, v34, v37
	v_add_f32_e32 v34, v36, v34
	v_fmamk_f32 v34, v34, 0x3b000000, v161
	v_mul_f32_e32 v35, 0x4b800000, v34
	v_cmp_gt_f32_e32 vcc, s81, v34
	s_nop 1
	v_cndmask_b32_e32 v34, v34, v35, vcc
	v_rsq_f32_e32 v36, v34
	v_add_co_u32_e64 v34, s[4:5], s64, v48
	v_mul_f32_e32 v37, 0x45800000, v36
	v_cndmask_b32_e32 v36, v36, v37, vcc
	v_pk_mul_f32 v[22:23], v[22:23], v[36:37] op_sel_hi:[1,0]
	v_pk_mul_f32 v[24:25], v[24:25], v[36:37] op_sel_hi:[1,0]
	v_pk_mul_f32 v[38:39], v[18:19], v[36:37] op_sel_hi:[1,0]
	v_pk_mul_f32 v[32:33], v[32:33], v[36:37] op_sel_hi:[1,0]
	v_pk_mul_f32 v[30:31], v[30:31], v[36:37] op_sel_hi:[1,0]
	v_pk_mul_f32 v[28:29], v[28:29], v[36:37] op_sel_hi:[1,0]
	v_pk_mul_f32 v[26:27], v[26:27], v[36:37] op_sel_hi:[1,0]
	v_pk_mul_f32 v[36:37], v[20:21], v[36:37] op_sel_hi:[1,0]
	v_cvt_pk_bf16_f32 v22, v22, v23
	v_cvt_pk_bf16_f32 v23, v24, v25
	v_cvt_pk_bf16_f32 v24, v38, v39
	v_cvt_pk_bf16_f32 v25, v36, v37
	v_cndmask_b32_e64 v21, v22, v24, s[0:1]
	v_cvt_pk_bf16_f32 v20, v26, v27
	s_nop 1
	v_mov_b32_dpp v26, v21 quad_perm:[1,0,3,2] row_mask:0xf bank_mask:0xf
	v_cndmask_b32_e64 v21, v23, v25, s[0:1]
	s_nop 1
	v_mov_b32_dpp v27, v21 quad_perm:[1,0,3,2] row_mask:0xf bank_mask:0xf
	v_cvt_pk_bf16_f32 v18, v30, v31
	v_cvt_pk_bf16_f32 v19, v32, v33
	v_cvt_pk_bf16_f32 v21, v28, v29
	global_store_dwordx4 v[46:47], v[18:21], off
	v_addc_co_u32_e64 v35, s[4:5], 0, v49, s[4:5]
	s_waitcnt lgkmcnt(1)
; template <class Epi, bool SEG = false>
; __device__ __forceinline__ void gemm_phase(LAS unsigned char* lds, const Gemm g, const StaticOrder& S, const Epi& E, const float* stat2 = nullptr) {
;     ...
;         if (wr == 0) PG8_BAR;
;         if constexpr (SEG) seg_scale(acc, lds, ui & 1, 2, wr, fr);
;         E(acc, cur, wr, wc, fr, fq);
;         if constexpr (SEG) { if (has_next) seg_fill(lds, stat2, nxt.pm, (ui + 1) & 1); }
;         if (!has_next) break;
; #pragma unroll
;         for (int a = 0; a < 2; ++a)
; #pragma unroll
;             for (int b = 0; b < 2; ++b)
; #pragma unroll
;     __device__ __forceinline__ void operator()(const Acc& acc, const pg8::Unit& u, int wr, int wc, int fr, int fq) const {
;     ...
;                 const int row = row0 + ai * 128 + m * 16, b = row >> 12, s = row & 4095;
;                 const f32x4 s0 = *(const f32x4*)(stat + (size_t)row * 16 + 8), s1 = *(const f32x4*)(stat + (size_t)row * 16 + 12);
;                 const float rs = rsqrtf(((s0[0] + s0[1]) + (s0[2] + s0[3]) + (s1[0] + s1[1]) + (s1[2] + s1[3])) * (1.0f / 512.0f) + EPS);
;                 const size_t bh = (size_t)(b * 8 + h);
;                 *(u32x4*)(KN + (bh * 4096 + s) * 128 + wc * 32 + 8 * fq) = pack8(acc[ai][0][m][0] * rs, acc[ai][0][m][1] * rs);
;                 { const unsigned q0 = cvt_pk_bf16(acc[ai][1][m][0][0] * rs, acc[ai][1][m][0][1] * rs), q1 = cvt_pk_bf16(acc[ai][1][m][0][2] * rs, acc[ai][1][m][0][3] * rs),
;                                  q2 = cvt_pk_bf16(acc[ai][1][m][1][0] * rs, acc[ai][1][m][1][1] * rs), q3 = cvt_pk_bf16(acc[ai][1][m][1][2] * rs, acc[ai][1][m][1][3] * rs);
;                   const bool odd = fr & 1;
;                   const unsigned mine0 = odd ? q2 : q0, mine1 = odd ? q3 : q1, send0 = odd ? q0 : q2, send1 = odd ? q1 : q3;
;                   const unsigned oth0 = (unsigned)__shfl_xor((int)send0, 1), oth1 = (unsigned)__shfl_xor((int)send1, 1);
;                   const unsigned lo0 = odd ? oth0 : mine0, hi0 = odd ? mine0 : oth0, lo1 = odd ? oth1 : mine1, hi1 = odd ? mine1 : oth1;
;                   unsigned* vp = (unsigned*)(VT + (bh * 128 + wc * 32 + 8 * fq + (odd ? 4 : 0)) * 4096 + (s & ~1));
;                   vp[0 * 2048] = (lo0 & 0xffffu) | (hi0 << 16); vp[1 * 2048] = (lo0 >> 16) | (hi0 & 0xffff0000u);
;                   vp[2 * 2048] = (lo1 & 0xffffu) | (hi1 << 16); vp[3 * 2048] = (lo1 >> 16) | (hi1 & 0xffff0000u); }
	v_cndmask_b32_e64 v19, v24, v26, s[0:1]
	v_cndmask_b32_e64 v18, v26, v22, s[0:1]
	s_waitcnt lgkmcnt(0)
	v_cndmask_b32_e64 v20, v27, v23, s[0:1]
	v_cndmask_b32_e64 v21, v25, v27, s[0:1]
	v_lshlrev_b32_e32 v22, 16, v19
	v_lshrrev_b32_e32 v23, 16, v18
	v_lshlrev_b32_e32 v24, 16, v21
	v_lshrrev_b32_e32 v25, 16, v20
	v_and_or_b32 v18, v18, s82, v22
	v_and_or_b32 v19, v19, s83, v23
	v_and_or_b32 v20, v20, s82, v24
	v_and_or_b32 v21, v21, s83, v25
	global_store_dword v[48:49], v18, off
	global_store_dword v[50:51], v19, off
	global_store_dword v[52:53], v20, off
	global_store_dword v[34:35], v21, off
	v_lshlrev_b32_e32 v26, 8, v42
	v_and_b32_e32 v28, 0xffe, v42
	v_and_b32_e32 v138, 0xfff00, v26
	v_lshl_add_u64 v[26:27], v[68:69], 0, v[138:139]
	v_lshlrev_b32_e32 v138, 1, v28
	v_lshl_add_u64 v[28:29], v[66:67], 0, v[138:139]
	v_add_co_u32_e32 v30, vcc, s62, v28
	v_lshl_add_u64 v[26:27], v[26:27], 0, s[12:13]
	s_nop 0
	v_addc_co_u32_e32 v31, vcc, 0, v29, vcc
	v_add_co_u32_e32 v32, vcc, 0x4000, v28
	v_lshl_add_u64 v[26:27], v[26:27], 0, v[150:151]
	s_nop 0
	v_addc_co_u32_e32 v33, vcc, 0, v29, vcc
	v_add_co_u32_e32 v34, vcc, 0x6000, v28
	v_mov_b32_e32 v18, v234
	v_mov_b32_e32 v19, v235
	v_mov_b32_e32 v20, v236
	v_mov_b32_e32 v21, v237
	v_mov_b32_e32 v36, v19
	v_mov_b32_e32 v37, v20
	v_mov_b32_e32 v19, v21
	v_mov_b32_e32 v22, v238
	v_mov_b32_e32 v23, v239
	v_mov_b32_e32 v24, v240
	v_mov_b32_e32 v25, v241
	v_mov_b32_e32 v20, v24
	v_mov_b32_e32 v21, v22
	v_mov_b32_e32 v22, v25
	v_pk_add_f32 v[18:19], v[36:37], v[18:19]
	v_pk_add_f32 v[20:21], v[20:21], v[22:23]
	v_add_f32_e32 v18, v18, v19
	v_add_f32_e32 v18, v18, v21
	v_add_f32_e32 v18, v20, v18
	v_fmamk_f32 v18, v18, 0x3b000000, v161
	v_mul_f32_e32 v19, 0x4b800000, v18
	v_cmp_gt_f32_e64 s[4:5], s81, v18
	v_addc_co_u32_e32 v35, vcc, 0, v29, vcc
	s_nop 0
	v_cndmask_b32_e64 v18, v18, v19, s[4:5]
	v_rsq_f32_e32 v18, v18
	s_and_b64 vcc, exec, s[2:3]
	s_mov_b64 s[2:3], -1
	v_mul_f32_e32 v19, 0x45800000, v18
	v_cndmask_b32_e64 v18, v18, v19, s[4:5]
	v_pk_mul_f32 v[6:7], v[6:7], v[18:19] op_sel_hi:[1,0]
	v_pk_mul_f32 v[8:9], v[8:9], v[18:19] op_sel_hi:[1,0]
	v_pk_mul_f32 v[20:21], v[2:3], v[18:19] op_sel_hi:[1,0]
	v_pk_mul_f32 v[16:17], v[16:17], v[18:19] op_sel_hi:[1,0]
	v_pk_mul_f32 v[14:15], v[14:15], v[18:19] op_sel_hi:[1,0]
	v_pk_mul_f32 v[12:13], v[12:13], v[18:19] op_sel_hi:[1,0]
	v_pk_mul_f32 v[10:11], v[10:11], v[18:19] op_sel_hi:[1,0]
	v_pk_mul_f32 v[18:19], v[4:5], v[18:19] op_sel_hi:[1,0]
	v_cvt_pk_bf16_f32 v6, v6, v7
	v_cvt_pk_bf16_f32 v7, v8, v9
	v_cvt_pk_bf16_f32 v8, v20, v21
	v_cvt_pk_bf16_f32 v9, v18, v19
	v_cndmask_b32_e64 v5, v6, v8, s[0:1]
	v_cvt_pk_bf16_f32 v4, v10, v11
	s_nop 1
	v_mov_b32_dpp v10, v5 quad_perm:[1,0,3,2] row_mask:0xf bank_mask:0xf
	v_cndmask_b32_e64 v5, v7, v9, s[0:1]
	s_nop 1
	v_mov_b32_dpp v11, v5 quad_perm:[1,0,3,2] row_mask:0xf bank_mask:0xf
	v_cvt_pk_bf16_f32 v2, v14, v15
	v_cvt_pk_bf16_f32 v3, v16, v17
	v_cvt_pk_bf16_f32 v5, v12, v13
	global_store_dwordx4 v[26:27], v[2:5], off
	s_waitcnt lgkmcnt(1)
	s_nop 0
	v_cndmask_b32_e64 v3, v8, v10, s[0:1]
	v_cndmask_b32_e64 v2, v10, v6, s[0:1]
	s_waitcnt lgkmcnt(0)
	v_cndmask_b32_e64 v4, v11, v7, s[0:1]
	v_cndmask_b32_e64 v5, v9, v11, s[0:1]
	v_lshlrev_b32_e32 v6, 16, v3
	v_lshrrev_b32_e32 v7, 16, v2
	v_lshlrev_b32_e32 v8, 16, v5
	v_lshrrev_b32_e32 v9, 16, v4
	v_and_or_b32 v2, v2, s82, v6
	v_and_or_b32 v3, v3, s83, v7
	v_and_or_b32 v4, v4, s82, v8
	v_and_or_b32 v5, v5, s83, v9
	global_store_dword v[28:29], v2, off
	global_store_dword v[30:31], v3, off
	global_store_dword v[32:33], v4, off
	global_store_dword v[34:35], v5, off
	s_cbranch_vccnz .LBB0_713
	s_andn2_b64 vcc, exec, s[14:15]
	s_cbranch_vccnz .LBB0_712
	s_barrier
	s_branch .LBB0_712
